# merge GEMM epilogue, first half: counted vmcnt ladder (7,6,6,5,5,4,4,3) instead of one vmcnt(0) behind the gate/merged loads
# speedup vs baseline: 1.0052x; 1.0040x over previous
; __device__ __forceinline__ unsigned pk2_(float lo, float hi) { f32x2_t v = {lo, hi}; bf16x2_t b = __builtin_convertvector(v, bf16x2_t); return __builtin_bit_cast(unsigned, b); }
;     __device__ __forceinline__ void operator()(const f32x4 (&acc)[2][2][4][2], const Unit& u, int wr, int wc, int fr, int fq) const {
;     ...
;             for (int m = 0; m < 4; ++m) { const int rl = wr * 64 + fr + ai * HALF + m * 16; bf16_t* mp2 = Mg + (size_t)(u.pm * BM + rl) * ldm + col0;
; #pragma unroll
;                 for (int bj = 0; bj < 2; ++bj) { const f32x4 v0 = acc[ai][bj][m][0], v1 = acc[ai][bj][m][1]; const u32x4 g = gw[m][bj], o = ow[m][bj];
;                     u32x4 w; w.x = pk2_(bflo(o.x) + bflo(g.x) * v0[0], bfhi(o.x) + bfhi(g.x) * v0[1]); w.y = pk2_(bflo(o.y) + bflo(g.y) * v0[2], bfhi(o.y) + bfhi(g.y) * v0[3]);
;                     w.z = pk2_(bflo(o.z) + bflo(g.z) * v1[0], bfhi(o.z) + bfhi(g.z) * v1[1]); w.w = pk2_(bflo(o.w) + bflo(g.w) * v1[2], bfhi(o.w) + bfhi(g.w) * v1[3]);
;                     *(u32x4*)(mp2 + bj * HALF) = w; } }
.LBB0_1266:
	s_waitcnt vmcnt(7)
	v_lshlrev_b32_e32 v232, 16, v186
	v_and_b32_e32 v233, 0xffff0000, v186
	v_lshlrev_b32_e32 v240, 16, v138
	v_and_b32_e32 v241, 0xffff0000, v138
	v_lshlrev_b32_e32 v186, 16, v187
	v_and_b32_e32 v187, 0xffff0000, v187
	v_lshlrev_b32_e32 v138, 16, v139
	v_and_b32_e32 v139, 0xffff0000, v139
	v_pk_fma_f32 v[126:127], v[126:127], v[240:241], v[232:233]
	v_pk_fma_f32 v[128:129], v[128:129], v[138:139], v[186:187]
	v_cvt_pk_bf16_f32 v126, v126, v127
	v_cvt_pk_bf16_f32 v127, v128, v129
	v_lshlrev_b32_e32 v128, 16, v188
	v_and_b32_e32 v129, 0xffff0000, v188
	v_lshlrev_b32_e32 v138, 16, v140
	v_and_b32_e32 v139, 0xffff0000, v140
	v_pk_fma_f32 v[122:123], v[122:123], v[138:139], v[128:129]
	v_lshlrev_b32_e32 v138, 16, v141
	v_cvt_pk_bf16_f32 v128, v122, v123
	v_lshlrev_b32_e32 v122, 16, v189
	v_and_b32_e32 v123, 0xffff0000, v189
	v_and_b32_e32 v139, 0xffff0000, v141
	v_pk_fma_f32 v[122:123], v[124:125], v[138:139], v[122:123]
	s_waitcnt vmcnt(6)
	v_lshlrev_b32_e32 v124, 16, v154
	v_cvt_pk_bf16_f32 v129, v122, v123
	v_lshlrev_b32_e32 v122, 16, v162
	v_and_b32_e32 v123, 0xffff0000, v162
	v_and_b32_e32 v125, 0xffff0000, v154
	v_pk_fma_f32 v[118:119], v[118:119], v[124:125], v[122:123]
	v_lshlrev_b32_e32 v122, 16, v163
	v_and_b32_e32 v123, 0xffff0000, v163
	v_lshlrev_b32_e32 v124, 16, v155
	v_and_b32_e32 v125, 0xffff0000, v155
	v_pk_fma_f32 v[120:121], v[120:121], v[124:125], v[122:123]
	v_cvt_pk_bf16_f32 v118, v118, v119
	v_cvt_pk_bf16_f32 v119, v120, v121
	v_lshlrev_b32_e32 v120, 16, v164
	v_and_b32_e32 v121, 0xffff0000, v164
	v_lshlrev_b32_e32 v122, 16, v156
	v_and_b32_e32 v123, 0xffff0000, v156
	v_pk_fma_f32 v[114:115], v[114:115], v[122:123], v[120:121]
	v_lshlrev_b32_e32 v122, 16, v157
	v_cvt_pk_bf16_f32 v120, v114, v115
	v_lshlrev_b32_e32 v114, 16, v165
	v_and_b32_e32 v115, 0xffff0000, v165
	v_and_b32_e32 v123, 0xffff0000, v157
	v_lshl_add_u64 v[230:231], v[230:231], 1, v[210:211]
	v_lshlrev_b64 v[228:229], 1, v[228:229]
	v_pk_fma_f32 v[114:115], v[116:117], v[122:123], v[114:115]
	v_lshl_add_u64 v[230:231], v[230:231], 0, v[228:229]
	v_cvt_pk_bf16_f32 v121, v114, v115
	global_store_dwordx4 v[230:231], v[118:121], off offset:256
	s_waitcnt vmcnt(6)
	v_lshlrev_b32_e32 v116, 16, v190
	v_and_b32_e32 v117, 0xffff0000, v190
	v_lshlrev_b32_e32 v118, 16, v178
	v_and_b32_e32 v119, 0xffff0000, v178
	v_pk_fma_f32 v[110:111], v[110:111], v[118:119], v[116:117]
	v_lshlrev_b32_e32 v116, 16, v191
	v_and_b32_e32 v117, 0xffff0000, v191
	v_lshlrev_b32_e32 v118, 16, v179
	v_and_b32_e32 v119, 0xffff0000, v179
	v_pk_fma_f32 v[112:113], v[112:113], v[118:119], v[116:117]
	v_cvt_pk_bf16_f32 v110, v110, v111
	v_cvt_pk_bf16_f32 v111, v112, v113
	v_lshlrev_b32_e32 v112, 16, v192
	v_and_b32_e32 v113, 0xffff0000, v192
	v_lshlrev_b32_e32 v116, 16, v180
	v_and_b32_e32 v117, 0xffff0000, v180
	v_pk_fma_f32 v[106:107], v[106:107], v[116:117], v[112:113]
	v_lshlrev_b32_e32 v116, 16, v181
	v_cvt_pk_bf16_f32 v112, v106, v107
	v_lshlrev_b32_e32 v106, 16, v193
	v_and_b32_e32 v107, 0xffff0000, v193
	v_and_b32_e32 v117, 0xffff0000, v181
	v_pk_fma_f32 v[106:107], v[108:109], v[116:117], v[106:107]
	s_waitcnt vmcnt(5)
	v_lshlrev_b32_e32 v108, 16, v158
	v_cvt_pk_bf16_f32 v113, v106, v107
	v_lshlrev_b32_e32 v106, 16, v142
	v_and_b32_e32 v107, 0xffff0000, v142
	v_and_b32_e32 v109, 0xffff0000, v158
	v_pk_fma_f32 v[102:103], v[102:103], v[108:109], v[106:107]
	v_lshlrev_b32_e32 v106, 16, v143
	v_and_b32_e32 v107, 0xffff0000, v143
	v_lshlrev_b32_e32 v108, 16, v159
	v_and_b32_e32 v109, 0xffff0000, v159
	v_pk_fma_f32 v[104:105], v[104:105], v[108:109], v[106:107]
	v_cvt_pk_bf16_f32 v102, v102, v103
	v_cvt_pk_bf16_f32 v103, v104, v105
	v_lshlrev_b32_e32 v104, 16, v144
	v_and_b32_e32 v105, 0xffff0000, v144
	v_lshlrev_b32_e32 v106, 16, v160
	v_and_b32_e32 v107, 0xffff0000, v160
	v_pk_fma_f32 v[98:99], v[98:99], v[106:107], v[104:105]
	v_lshlrev_b32_e32 v106, 16, v161
	v_cvt_pk_bf16_f32 v104, v98, v99
	v_lshlrev_b32_e32 v98, 16, v145
	v_and_b32_e32 v99, 0xffff0000, v145
	v_and_b32_e32 v107, 0xffff0000, v161
	v_mad_i64_i32 v[114:115], s[4:5], v238, s34, v[210:211]
	v_pk_fma_f32 v[98:99], v[100:101], v[106:107], v[98:99]
	v_lshl_add_u64 v[114:115], v[114:115], 0, v[228:229]
	v_cvt_pk_bf16_f32 v105, v98, v99
	global_store_dwordx4 v[114:115], v[102:105], off offset:256
	s_waitcnt vmcnt(5)
; __device__ __forceinline__ unsigned pk2_(float lo, float hi) { f32x2_t v = {lo, hi}; bf16x2_t b = __builtin_convertvector(v, bf16x2_t); return __builtin_bit_cast(unsigned, b); }
;     __device__ __forceinline__ void operator()(const f32x4 (&acc)[2][2][4][2], const Unit& u, int wr, int wc, int fr, int fq) const {
;     ...
;             for (int m = 0; m < 4; ++m) { const int rl = wr * 64 + fr + ai * HALF + m * 16;
;                 const bf16_t* gp = gm.at(u.pm, rl, u.sel * 8 + u.pn, wc * 32 + 8 * fq); const bf16_t* mp2 = Mg + (size_t)(u.pm * BM + rl) * ldm + col0;
; #pragma unroll
;                 for (int bj = 0; bj < 2; ++bj) { gw[m][bj] = *(const u32x4*)(gp + bj * HALF); ow[m][bj] = (u32x4){0u, 0u, 0u, 0u}; if (u.sel > 0) ow[m][bj] = *(const u32x4*)(mp2 + bj * HALF); } }
;     ...
;             for (int m = 0; m < 4; ++m) { const int rl = wr * 64 + fr + ai * HALF + m * 16; bf16_t* mp2 = Mg + (size_t)(u.pm * BM + rl) * ldm + col0;
; #pragma unroll
;                 for (int bj = 0; bj < 2; ++bj) { const f32x4 v0 = acc[ai][bj][m][0], v1 = acc[ai][bj][m][1]; const u32x4 g = gw[m][bj], o = ow[m][bj];
;                     u32x4 w; w.x = pk2_(bflo(o.x) + bflo(g.x) * v0[0], bfhi(o.x) + bfhi(g.x) * v0[1]); w.y = pk2_(bflo(o.y) + bflo(g.y) * v0[2], bfhi(o.y) + bfhi(g.y) * v0[3]);
;                     w.z = pk2_(bflo(o.z) + bflo(g.z) * v1[0], bfhi(o.z) + bfhi(g.z) * v1[1]); w.w = pk2_(bflo(o.w) + bflo(g.w) * v1[2], bfhi(o.w) + bfhi(g.w) * v1[3]);
;                     *(u32x4*)(mp2 + bj * HALF) = w; } }
	v_lshlrev_b32_e32 v100, 16, v182
	v_and_b32_e32 v101, 0xffff0000, v182
	v_lshlrev_b32_e32 v102, 16, v170
	v_and_b32_e32 v103, 0xffff0000, v170
	v_pk_fma_f32 v[94:95], v[94:95], v[102:103], v[100:101]
	v_lshlrev_b32_e32 v100, 16, v183
	v_and_b32_e32 v101, 0xffff0000, v183
	v_lshlrev_b32_e32 v102, 16, v171
	v_and_b32_e32 v103, 0xffff0000, v171
	v_pk_fma_f32 v[96:97], v[96:97], v[102:103], v[100:101]
	v_cvt_pk_bf16_f32 v94, v94, v95
	v_cvt_pk_bf16_f32 v95, v96, v97
	v_lshlrev_b32_e32 v96, 16, v184
	v_and_b32_e32 v97, 0xffff0000, v184
	v_lshlrev_b32_e32 v100, 16, v172
	v_and_b32_e32 v101, 0xffff0000, v172
	v_pk_fma_f32 v[90:91], v[90:91], v[100:101], v[96:97]
	v_lshlrev_b32_e32 v100, 16, v173
	v_cvt_pk_bf16_f32 v96, v90, v91
	v_lshlrev_b32_e32 v90, 16, v185
	v_and_b32_e32 v91, 0xffff0000, v185
	v_and_b32_e32 v101, 0xffff0000, v173
	v_pk_fma_f32 v[90:91], v[92:93], v[100:101], v[90:91]
	s_waitcnt vmcnt(4)
	v_lshlrev_b32_e32 v92, 16, v150
	v_cvt_pk_bf16_f32 v97, v90, v91
	v_lshlrev_b32_e32 v90, 16, v134
	v_and_b32_e32 v91, 0xffff0000, v134
	v_and_b32_e32 v93, 0xffff0000, v150
	v_pk_fma_f32 v[86:87], v[86:87], v[92:93], v[90:91]
	v_lshlrev_b32_e32 v90, 16, v135
	v_and_b32_e32 v91, 0xffff0000, v135
	v_lshlrev_b32_e32 v92, 16, v151
	v_and_b32_e32 v93, 0xffff0000, v151
	v_pk_fma_f32 v[88:89], v[88:89], v[92:93], v[90:91]
	v_cvt_pk_bf16_f32 v86, v86, v87
	v_cvt_pk_bf16_f32 v87, v88, v89
	v_lshlrev_b32_e32 v88, 16, v136
	v_and_b32_e32 v89, 0xffff0000, v136
	v_lshlrev_b32_e32 v90, 16, v152
	v_and_b32_e32 v91, 0xffff0000, v152
	v_pk_fma_f32 v[82:83], v[82:83], v[90:91], v[88:89]
	v_lshlrev_b32_e32 v90, 16, v153
	v_cvt_pk_bf16_f32 v88, v82, v83
	v_lshlrev_b32_e32 v82, 16, v137
	v_and_b32_e32 v83, 0xffff0000, v137
	v_and_b32_e32 v91, 0xffff0000, v153
	v_mad_i64_i32 v[98:99], s[4:5], v253, s34, v[210:211]
	v_pk_fma_f32 v[82:83], v[84:85], v[90:91], v[82:83]
	v_lshl_add_u64 v[98:99], v[98:99], 0, v[228:229]
	v_cvt_pk_bf16_f32 v89, v82, v83
	global_store_dwordx4 v[98:99], v[86:89], off offset:256
	s_waitcnt vmcnt(4)
	v_lshlrev_b32_e32 v84, 16, v174
	v_and_b32_e32 v85, 0xffff0000, v174
	v_lshlrev_b32_e32 v86, 16, v166
	v_and_b32_e32 v87, 0xffff0000, v166
	v_pk_fma_f32 v[78:79], v[78:79], v[86:87], v[84:85]
	v_lshlrev_b32_e32 v84, 16, v175
	v_and_b32_e32 v85, 0xffff0000, v175
	v_lshlrev_b32_e32 v86, 16, v167
	v_and_b32_e32 v87, 0xffff0000, v167
	v_pk_fma_f32 v[80:81], v[80:81], v[86:87], v[84:85]
	v_cvt_pk_bf16_f32 v78, v78, v79
	v_cvt_pk_bf16_f32 v79, v80, v81
	v_lshlrev_b32_e32 v80, 16, v176
	v_and_b32_e32 v81, 0xffff0000, v176
	v_lshlrev_b32_e32 v84, 16, v168
	v_and_b32_e32 v85, 0xffff0000, v168
	v_pk_fma_f32 v[74:75], v[74:75], v[84:85], v[80:81]
	v_lshlrev_b32_e32 v84, 16, v169
	v_cvt_pk_bf16_f32 v80, v74, v75
	v_lshlrev_b32_e32 v74, 16, v177
	v_and_b32_e32 v75, 0xffff0000, v177
	v_and_b32_e32 v85, 0xffff0000, v169
	v_pk_fma_f32 v[74:75], v[76:77], v[84:85], v[74:75]
	s_waitcnt vmcnt(3)
	v_lshlrev_b32_e32 v76, 16, v146
	v_cvt_pk_bf16_f32 v81, v74, v75
	v_lshlrev_b32_e32 v74, 16, v130
	v_and_b32_e32 v75, 0xffff0000, v130
	v_and_b32_e32 v77, 0xffff0000, v146
	v_pk_fma_f32 v[70:71], v[70:71], v[76:77], v[74:75]
	v_lshlrev_b32_e32 v74, 16, v131
	v_and_b32_e32 v75, 0xffff0000, v131
	v_lshlrev_b32_e32 v76, 16, v147
	v_and_b32_e32 v77, 0xffff0000, v147
	v_pk_fma_f32 v[72:73], v[72:73], v[76:77], v[74:75]
	v_cvt_pk_bf16_f32 v70, v70, v71
	v_cvt_pk_bf16_f32 v71, v72, v73
	v_lshlrev_b32_e32 v72, 16, v132
	v_and_b32_e32 v73, 0xffff0000, v132
	v_lshlrev_b32_e32 v74, 16, v148
	v_and_b32_e32 v75, 0xffff0000, v148
	v_pk_fma_f32 v[66:67], v[66:67], v[74:75], v[72:73]
	v_lshlrev_b32_e32 v74, 16, v149
	v_cvt_pk_bf16_f32 v72, v66, v67
	v_lshlrev_b32_e32 v66, 16, v133
	v_and_b32_e32 v67, 0xffff0000, v133
	v_and_b32_e32 v75, 0xffff0000, v149
	v_mad_i64_i32 v[82:83], s[4:5], v17, s34, v[210:211]
	v_pk_fma_f32 v[66:67], v[68:69], v[74:75], v[66:67]
	v_lshl_add_u64 v[82:83], v[82:83], 0, v[228:229]
	v_cvt_pk_bf16_f32 v73, v66, v67
	global_store_dwordx4 v[230:231], v[126:129], off
	global_store_dwordx4 v[114:115], v[110:113], off
	global_store_dwordx4 v[98:99], v[94:97], off
	global_store_dwordx4 v[82:83], v[78:81], off
	global_store_dwordx4 v[82:83], v[70:73], off offset:256
	v_add_u32_e32 v66, s21, v248
	s_mov_b64 s[4:5], -1
	s_and_b64 vcc, exec, s[38:39]
	v_ashrrev_i32_e32 v17, 31, v66
	s_cbranch_vccnz .LBB0_1268
	v_add_u32_e32 v67, s20, v248
	s_movk_i32 s3, 0x1800
	v_mad_i64_i32 v[68:69], s[4:5], v67, s3, v[220:221]
	s_mov_b64 s[4:5], 0
